# up-projection quarter units + conv tail load hoisting, every hot loop kept at the code alignment of the quarter-first version
# speedup vs baseline: 1.0024x; 1.0024x over previous
; template <class Epi, class Sched, bool ALIGN_EPI = false, bool SP2 = false>
; __device__ __forceinline__ void gemm_phase(PG8_LAS unsigned char* lds, const Gemm g, const Sched& S, const Epi& E) {
;     ...
;     f32x4 acc[2][2][4][2];
; #pragma unroll
;     for (int a = 0; a < 2; ++a)
; #pragma unroll
;         for (int b = 0; b < 2; ++b)
; #pragma unroll
;             for (int m = 0; m < 4; ++m)
; #pragma unroll
;                 for (int n = 0; n < 2; ++n) acc[a][b][m][n] = (f32x4){0.f, 0.f, 0.f, 0.f};
;     bf16x8 At[4][2], B0[2][2], B1[2][2];
;     const char* cA = (const char*)g.A + (size_t)cur.pm * tstep; const char* cB = (const char*)g.Bt + (size_t)cur.pn * tstep;
;     ...
;         const bool has_next = S.next(ui + 1, nxt);
;         const char* nA = has_next ? (const char*)g.A + (size_t)nxt.pm * tstep : cA; const char* nB = has_next ? (const char*)g.Bt + (size_t)nxt.pn * tstep : cB;
.LBB0_162:
	s_ashr_i32 s21, s20, 31
	s_lshl_b64 s[22:23], s[20:21], 19
	s_add_u32 s22, s46, s22
	s_addc_u32 s23, s47, s23
	s_and_b64 s[24:25], s[6:7], exec
	s_cselect_b32 s21, s23, s31
	s_cselect_b32 s27, s22, s30
	s_ashr_i32 s19, s18, 31
	s_lshl_b64 s[24:25], s[18:19], 19
	s_add_u32 s24, s48, s24
	s_addc_u32 s25, s49, s25
	s_and_b64 s[40:41], s[6:7], exec
	s_cselect_b32 s19, s25, s35
	s_cselect_b32 s50, s24, s34
	s_add_u32 s30, s30, 0x40080
	s_addc_u32 s31, s31, 0
	s_add_u32 s52, s34, 0x100
	v_mov_b32_e32 v2, 0
	s_addc_u32 s54, s35, 0
	s_mov_b32 s62, -2
	v_mov_b32_e32 v3, v2
	v_mov_b32_e32 v4, v2
	v_mov_b32_e32 v5, v2
	v_mov_b32_e32 v6, v2
	v_mov_b32_e32 v7, v2
	v_mov_b32_e32 v8, v2
	v_mov_b32_e32 v9, v2
	v_mov_b32_e32 v18, v2
	v_mov_b32_e32 v19, v2
	v_mov_b32_e32 v20, v2
	v_mov_b32_e32 v21, v2
	v_mov_b32_e32 v22, v2
	v_mov_b32_e32 v23, v2
	v_mov_b32_e32 v24, v2
	v_mov_b32_e32 v25, v2
	v_mov_b32_e32 v34, v2
	v_mov_b32_e32 v35, v2
	v_mov_b32_e32 v36, v2
	v_mov_b32_e32 v37, v2
	v_mov_b32_e32 v38, v2
	v_mov_b32_e32 v39, v2
	v_mov_b32_e32 v40, v2
	v_mov_b32_e32 v41, v2
	v_mov_b32_e32 v50, v2
	v_mov_b32_e32 v51, v2
	v_mov_b32_e32 v52, v2
	v_mov_b32_e32 v53, v2
	v_mov_b32_e32 v54, v2
	v_mov_b32_e32 v55, v2
	v_mov_b32_e32 v56, v2
	v_mov_b32_e32 v57, v2
	v_mov_b32_e32 v10, v2
	v_mov_b32_e32 v11, v2
	v_mov_b32_e32 v12, v2
	v_mov_b32_e32 v13, v2
	v_mov_b32_e32 v14, v2
	v_mov_b32_e32 v15, v2
	v_mov_b32_e32 v16, v2
	v_mov_b32_e32 v17, v2
	v_mov_b32_e32 v26, v2
	v_mov_b32_e32 v27, v2
	v_mov_b32_e32 v28, v2
	v_mov_b32_e32 v29, v2
	v_mov_b32_e32 v30, v2
	v_mov_b32_e32 v31, v2
	v_mov_b32_e32 v32, v2
	v_mov_b32_e32 v33, v2
	v_mov_b32_e32 v42, v2
	v_mov_b32_e32 v43, v2
	v_mov_b32_e32 v44, v2
	v_mov_b32_e32 v45, v2
	v_mov_b32_e32 v46, v2
	v_mov_b32_e32 v47, v2
	v_mov_b32_e32 v48, v2
	v_mov_b32_e32 v49, v2
	v_mov_b32_e32 v58, v2
	v_mov_b32_e32 v59, v2
	v_mov_b32_e32 v60, v2
	v_mov_b32_e32 v61, v2
	v_mov_b32_e32 v62, v2
	v_mov_b32_e32 v63, v2
	v_mov_b32_e32 v64, v2
	v_mov_b32_e32 v65, v2
	v_mov_b32_e32 v66, v2
	v_mov_b32_e32 v67, v2
	v_mov_b32_e32 v68, v2
	v_mov_b32_e32 v69, v2
	v_mov_b32_e32 v70, v2
	v_mov_b32_e32 v71, v2
	v_mov_b32_e32 v72, v2
	v_mov_b32_e32 v73, v2
	v_mov_b32_e32 v82, v2
	v_mov_b32_e32 v83, v2
	v_mov_b32_e32 v84, v2
	v_mov_b32_e32 v85, v2
	v_mov_b32_e32 v86, v2
	v_mov_b32_e32 v87, v2
	v_mov_b32_e32 v88, v2
	v_mov_b32_e32 v89, v2
	v_mov_b32_e32 v98, v2
	v_mov_b32_e32 v99, v2
	v_mov_b32_e32 v100, v2
	v_mov_b32_e32 v101, v2
	v_mov_b32_e32 v102, v2
	v_mov_b32_e32 v103, v2
	v_mov_b32_e32 v104, v2
	v_mov_b32_e32 v105, v2
	v_mov_b32_e32 v114, v2
	v_mov_b32_e32 v115, v2
	v_mov_b32_e32 v116, v2
	v_mov_b32_e32 v117, v2
	v_mov_b32_e32 v118, v2
	v_mov_b32_e32 v119, v2
	v_mov_b32_e32 v120, v2
	v_mov_b32_e32 v121, v2
	v_mov_b32_e32 v74, v2
	v_mov_b32_e32 v75, v2
	v_mov_b32_e32 v76, v2
	v_mov_b32_e32 v77, v2
	v_mov_b32_e32 v78, v2
	v_mov_b32_e32 v79, v2
	v_mov_b32_e32 v80, v2
	v_mov_b32_e32 v81, v2
	v_mov_b32_e32 v90, v2
	v_mov_b32_e32 v91, v2
	v_mov_b32_e32 v92, v2
	v_mov_b32_e32 v93, v2
	v_mov_b32_e32 v94, v2
	v_mov_b32_e32 v95, v2
	v_mov_b32_e32 v96, v2
	v_mov_b32_e32 v97, v2
	v_mov_b32_e32 v106, v2
	v_mov_b32_e32 v107, v2
	v_mov_b32_e32 v108, v2
	v_mov_b32_e32 v109, v2
	v_mov_b32_e32 v110, v2
	v_mov_b32_e32 v111, v2
	v_mov_b32_e32 v112, v2
	v_mov_b32_e32 v113, v2
	v_mov_b32_e32 v122, v2
	v_mov_b32_e32 v123, v2
	v_mov_b32_e32 v124, v2
	v_mov_b32_e32 v125, v2
	v_mov_b32_e32 v126, v2
	v_mov_b32_e32 v127, v2
	v_mov_b32_e32 v128, v2
	v_mov_b32_e32 v129, v2
	s_and_b32 s98, s101, 7
	s_cmp_lg_u32 s98, 0
	s_cbranch_scc0 .LBB0_163
	s_and_b32 s98, s101, 7
	s_cmp_eq_u32 s98, 1
	s_cbranch_scc1 .Lkuq_1
	s_and_b32 s98, s101, 7
	s_cmp_eq_u32 s98, 2
	s_cbranch_scc1 .Lkuq_2
	s_and_b32 s98, s101, 7
	s_cmp_eq_u32 s98, 3
	s_cbranch_scc1 .Lkuq_3
	s_and_b32 s98, s101, 7
	s_cmp_eq_u32 s98, 4
	s_cbranch_scc1 .Lkuq_4
	s_and_b32 s98, s101, 7
	s_cmp_eq_u32 s98, 5
	s_cbranch_scc1 .Lku_a0
	s_branch .Lku_a1
	s_nop 0
	s_nop 0
	s_nop 0
	s_nop 0
	s_nop 0
	s_nop 0
	s_nop 0

; #define PG8_STAGE(bufoff, gbase, voff) do { _Pragma("unroll") for (int _i = 0; _i < 2; ++_i) \
;         __builtin_amdgcn_global_load_lds((const unsigned*)((const char*)(gbase) + (voff)[_i]), (PG8_LAS unsigned*)(lds + (bufoff) + ldsw + _i * 8192), 16, 0, 0); } while (0)
; #define PG8_BAR __builtin_amdgcn_s_barrier()
; template <class Epi, class Sched, bool ALIGN_EPI = false, bool SP2 = false>
; __device__ __forceinline__ void gemm_phase(PG8_LAS unsigned char* lds, const Gemm g, const Sched& S, const Epi& E) {
;     ...
;         PG8_STAGE(PG8_SB(1, 0), cB + kstep, voffB); PG8_STAGE(PG8_SA(1, 0), cA + kstep, voffA); PG8_STAGE(PG8_SB(1, 1), cB + hstep + kstep, voffB);
;         PG8_WAIT_V(6); PG8_BAR;
;     } else {
;         PG8_STAGE(PG8_SB(0, 0), cB, voffB); PG8_STAGE(PG8_SA(0, 0), cA, voffA); PG8_STAGE(PG8_SB(0, 1), cB + hstep, voffB); PG8_STAGE(PG8_SA(0, 1), cA + hstep, voffA);
;         if (wr == 1) PG8_BAR;
;         PG8_WAIT_V(4); PG8_BAR;
;         PG8_STAGE(PG8_SB(1, 0), cB + kstep, voffB); PG8_STAGE(PG8_SA(1, 0), cA + kstep, voffA); PG8_STAGE(PG8_SB(1, 1), cB + hstep + kstep, voffB);
;         PG8_WAIT_V(6); PG8_BAR;
;     __device__ __forceinline__ void operator()(const f32x4 (&acc)[2][2][4][2], const Unit& u, int wr, int wc, int fr, int fq) const {
;         const int pm = u.pm + pm0, pn = u.pn + pn0;
;         const bool lat = pm < 64; const int b = lat ? (pm >> 3) : (pm - 64); const int tokb = lat ? (pm & 7) * 256 : 2048;
;         const int rl0 = wr * 64 + fr, cl0 = wc * 32 + 4 * fq;
;         if (pn < 5) {
;             bf16_t* base; int ld;
;             if (pn < 4) { base = swq + pn * 256; ld = 1024; } else { base = swk; ld = 256; }
;             base += (size_t)(pm * 256 + rl0) * ld + cl0;
;             const float rot = lat ? 1.f : 0.f;
; #pragma unroll
;             for (int ai = 0; ai < 2; ++ai)
; #pragma unroll
;                 for (int m = 0; m < 4; ++m) {
;                     const int tok = tokb + rl0 + ai * 128 + m * 16;
;                     const float pos = rot * (float)((wc & 1) ? (tok & 63) : (tok >> 6));
;                     bf16_t* rp = base + (size_t)(ai * 128 + m * 16) * ld;
;                     float cs[4], sn[4];
; #pragma unroll
;                     for (int j = 0; j < 4; ++j) { const float a = pos * __builtin_amdgcn_exp2f(-(float)(4 * fq + j) * 0.830482023721841f); cs[j] = __cosf(a); sn[j] = __sinf(a); }
.LBB0_182:
	s_add_u32 s79, s6, 0x7f00000
	s_addc_u32 s80, s7, 0
	s_add_u32 s81, s6, 0x9f00000
	s_addc_u32 s82, s7, 0
	s_add_u32 s16, s6, 0xa800000
	s_addc_u32 s17, s7, 0
	s_and_b32 s20, s11, 3
	s_add_i32 m0, s50, 0x18000
	v_lshl_add_u64 v[8:9], v[8:9], 0, s[66:67]
	s_lshl_b32 s19, s18, 13
	s_lshl_b32 s21, s20, 12
	s_waitcnt vmcnt(2)
	s_barrier
	global_load_lds_dwordx4 v[8:9], off
	v_lshl_add_u64 v[6:7], v[6:7], 0, s[66:67]
	s_add_i32 m0, s50, 0x1a000
	s_add_i32 s83, s50, 0x8000
	s_add_i32 s84, s50, 0xa000
	global_load_lds_dwordx4 v[6:7], off
	v_lshl_add_u64 v[2:3], v[2:3], 0, s[66:67]
	s_mov_b32 m0, s83
	s_add_u32 s6, s34, 0x40080
	global_load_lds_dwordx4 v[2:3], off
	v_lshl_add_u64 v[2:3], v[4:5], 0, s[66:67]
	s_mov_b32 m0, s84
	s_addc_u32 s7, s35, 0
	global_load_lds_dwordx4 v[2:3], off
	s_add_i32 m0, s50, 0x1c000
	v_lshl_add_u64 v[2:3], s[6:7], 0, v[132:133]
	global_load_lds_dwordx4 v[2:3], off
	v_lshl_add_u64 v[2:3], s[6:7], 0, v[130:131]
	s_add_i32 m0, s50, 0x1e000
	v_and_b32_e32 v137, 15, v12
	global_load_lds_dwordx4 v[2:3], off
	v_bfe_u32 v2, v12, 4, 2
	v_lshlrev_b32_e32 v3, 4, v2
	v_lshlrev_b32_e32 v4, 2, v12
	v_lshl_or_b32 v3, v137, 6, v3
	v_and_b32_e32 v4, 32, v4
	v_lshlrev_b32_e32 v2, 2, v2
	v_bitop3_b32 v5, v3, s19, v4 bitop3:0xde
	v_bitop3_b32 v143, v3, s21, v4 bitop3:0xde
	v_cvt_f32_ubyte0_e32 v3, v2
	v_mul_f32_e32 v3, 0xbf549a78, v3
	v_exp_f32_e32 v145, v3
	v_or_b32_e32 v3, 1, v2
	v_cvt_f32_ubyte0_e32 v3, v3
	v_mul_f32_e32 v3, 0xbf549a78, v3
	v_lshl_or_b32 v136, s20, 5, v2
	v_exp_f32_e32 v147, v3
	v_or_b32_e32 v3, 2, v2
	v_or_b32_e32 v2, 3, v2
	v_cvt_f32_ubyte0_e32 v2, v2
	v_mul_f32_e32 v2, 0xbf549a78, v2
	v_cvt_f32_ubyte0_e32 v3, v3
	v_exp_f32_e32 v208, v2
	v_lshlrev_b32_e32 v2, 14, v13
	v_mul_f32_e32 v3, 0xbf549a78, v3
	v_and_b32_e32 v2, 0xffff8000, v2
	v_exp_f32_e32 v207, v3
	v_lshl_add_u32 v2, v14, 11, v2
	v_and_b32_e32 v3, 1, v13
	v_lshl_or_b32 v2, v3, 6, v2
	v_lshl_add_u32 v148, v15, 1, v2
	v_lshlrev_b32_e32 v2, 14, v0
	v_and_b32_e32 v2, 0xffff8000, v2
	s_waitcnt vmcnt(6)
	s_cmpk_lt_u32 s9, 0x100
	v_lshl_add_u32 v2, v10, 11, v2
	v_and_b32_e32 v0, 1, v0
	v_lshl_or_b32 v134, s18, 6, v137
	s_cselect_b64 s[18:19], -1, 0
	s_bitcmp0_b32 s9, 6
	v_lshl_or_b32 v0, v0, 6, v2
	s_sext_i32_i16 s29, s8
	s_mov_b32 s11, s65
	v_ashrrev_i32_e32 v135, 31, v134
	s_mov_b32 s52, 0
	s_cselect_b64 s[6:7], -1, 0
	v_or_b32_e32 v209, 16, v137
	v_or_b32_e32 v210, 32, v137
	v_or_b32_e32 v211, 48, v137
	v_mov_b32_e32 v149, v1
	v_lshl_add_u32 v150, v11, 1, v0
	v_mov_b32_e32 v151, v1
	v_add_u32_e32 v212, 0, v5
	s_barrier
	s_branch .LBB0_185
	s_nop 0
	s_nop 0
	s_nop 0
	s_nop 0
	s_nop 0
	s_nop 0
	s_nop 0
	s_nop 0
	s_nop 0
	s_nop 0
	s_nop 0
